# static attention schedule + redundant 24-wait-state nops removed before the row-max chain (distance to the last QK MFMA already exceeds 12 states)
# speedup vs baseline: 1.0162x; 1.0086x over previous
.LBB0_691:
	s_add_i32 s4, s21, -3
	s_min_u32 s54, s4, s43
	s_mul_hi_u32 s4, s54, 0x55555556
	s_mul_i32 s4, s4, 3
	s_sub_i32 s4, s54, s4
	v_lshl_add_u32 v64, s4, 14, v153
	ds_read_b128 v[140:143], v64
	ds_read_b128 v[132:135], v64 offset:512
	ds_read_b128 v[136:139], v64 offset:2048
	ds_read_b128 v[120:123], v64 offset:2560
	ds_read_b128 v[128:131], v64 offset:4096
	ds_read_b128 v[116:119], v64 offset:4608
	ds_read_b128 v[124:127], v64 offset:6144
	ds_read_b128 v[112:115], v64 offset:6656
	s_nop 0
	v_max3_f32 v64, v48, v32, v49
	v_max3_f32 v65, v33, v50, v34
	s_nop 0
	v_max3_f32 v64, v64, v51, v35
	v_max3_f32 v65, v65, v52, v36
	s_nop 0
	v_max3_f32 v64, v64, v53, v37
	v_max3_f32 v65, v65, v54, v38
	s_nop 0
	v_max3_f32 v64, v64, v55, v39
	v_max3_f32 v65, v65, v56, v40
	s_nop 0
	v_max3_f32 v64, v64, v57, v41
	v_max3_f32 v65, v65, v58, v42
	s_nop 0
	v_max3_f32 v64, v64, v59, v43
	v_max3_f32 v65, v65, v60, v44
	s_nop 0
	v_max3_f32 v64, v64, v61, v45
	v_max3_f32 v65, v65, v62, v46
	s_nop 0
	v_max3_f32 v64, v64, v63, v47
	s_nop 0
	s_nop 1
	s_nop 0
	v_max_f32_e32 v65, v65, v65
	v_max_f32_e32 v64, v64, v64
	v_max_f32_e32 v64, v64, v65
	v_mov_b32_e32 v65, v64
	s_nop 1
	v_permlane32_swap_b32_e32 v64, v65
	v_max_f32_e32 v65, v65, v65
	v_max_f32_e32 v64, v64, v64
	v_max_f32_e32 v64, v64, v65
	v_cmp_lt_f32_e32 vcc, s97, v64
	v_cmp_lg_f32_e64 s[4:5], s96, v64
	s_nop 0
	v_cndmask_b32_e64 v65, 0, 1, vcc
	v_cndmask_b32_e64 v66, 0, 1, s[4:5]
	v_cndmask_b32_e64 v65, v66, v65, s[2:3]
	v_and_b32_e32 v65, 1, v65
	v_cmp_eq_u32_e64 s[6:7], 1, v65
	v_cmp_ne_u32_e32 vcc, 0, v65
	s_cbranch_vccz .LBB0_693
	v_cndmask_b32_e64 v64, 0, v64, s[6:7]
	v_exp_f32_e64 v66, -v64
	s_or_b64 s[4:5], s[2:3], s[4:5]
	s_andn2_b64 s[2:3], s[2:3], exec
	s_and_b64 s[4:5], s[4:5], exec
	v_pk_add_f32 v[48:49], v[48:49], v[64:65] op_sel_hi:[1,0] neg_lo:[0,1] neg_hi:[0,1]
	v_pk_add_f32 v[32:33], v[32:33], v[64:65] op_sel_hi:[1,0] neg_lo:[0,1] neg_hi:[0,1]
	v_pk_add_f32 v[50:51], v[50:51], v[64:65] op_sel_hi:[1,0] neg_lo:[0,1] neg_hi:[0,1]
	v_pk_add_f32 v[34:35], v[34:35], v[64:65] op_sel_hi:[1,0] neg_lo:[0,1] neg_hi:[0,1]
	v_pk_add_f32 v[52:53], v[52:53], v[64:65] op_sel_hi:[1,0] neg_lo:[0,1] neg_hi:[0,1]
	v_pk_add_f32 v[36:37], v[36:37], v[64:65] op_sel_hi:[1,0] neg_lo:[0,1] neg_hi:[0,1]
	v_pk_add_f32 v[54:55], v[54:55], v[64:65] op_sel_hi:[1,0] neg_lo:[0,1] neg_hi:[0,1]
	v_pk_add_f32 v[38:39], v[38:39], v[64:65] op_sel_hi:[1,0] neg_lo:[0,1] neg_hi:[0,1]
	v_pk_add_f32 v[56:57], v[56:57], v[64:65] op_sel_hi:[1,0] neg_lo:[0,1] neg_hi:[0,1]
	v_pk_add_f32 v[40:41], v[40:41], v[64:65] op_sel_hi:[1,0] neg_lo:[0,1] neg_hi:[0,1]
	v_pk_add_f32 v[58:59], v[58:59], v[64:65] op_sel_hi:[1,0] neg_lo:[0,1] neg_hi:[0,1]
	v_pk_add_f32 v[42:43], v[42:43], v[64:65] op_sel_hi:[1,0] neg_lo:[0,1] neg_hi:[0,1]
	v_pk_add_f32 v[60:61], v[60:61], v[64:65] op_sel_hi:[1,0] neg_lo:[0,1] neg_hi:[0,1]
	v_pk_add_f32 v[44:45], v[44:45], v[64:65] op_sel_hi:[1,0] neg_lo:[0,1] neg_hi:[0,1]
	v_pk_add_f32 v[62:63], v[62:63], v[64:65] op_sel_hi:[1,0] neg_lo:[0,1] neg_hi:[0,1]
	v_pk_add_f32 v[46:47], v[46:47], v[64:65] op_sel_hi:[1,0] neg_lo:[0,1] neg_hi:[0,1]
	v_add_f32_e32 v154, v154, v64
	v_mul_f32_e32 v150, v150, v66
	v_pk_mul_f32 v[30:31], v[30:31], v[66:67] op_sel_hi:[1,0]
	v_pk_mul_f32 v[28:29], v[28:29], v[66:67] op_sel_hi:[1,0]
	v_pk_mul_f32 v[26:27], v[26:27], v[66:67] op_sel_hi:[1,0]
	v_pk_mul_f32 v[24:25], v[24:25], v[66:67] op_sel_hi:[1,0]
	v_pk_mul_f32 v[22:23], v[22:23], v[66:67] op_sel_hi:[1,0]
	v_pk_mul_f32 v[20:21], v[20:21], v[66:67] op_sel_hi:[1,0]
	v_pk_mul_f32 v[18:19], v[18:19], v[66:67] op_sel_hi:[1,0]
	v_pk_mul_f32 v[16:17], v[16:17], v[66:67] op_sel_hi:[1,0]
	v_pk_mul_f32 v[14:15], v[14:15], v[66:67] op_sel_hi:[1,0]
	v_pk_mul_f32 v[12:13], v[12:13], v[66:67] op_sel_hi:[1,0]
	v_pk_mul_f32 v[10:11], v[10:11], v[66:67] op_sel_hi:[1,0]
	v_pk_mul_f32 v[8:9], v[8:9], v[66:67] op_sel_hi:[1,0]
	v_pk_mul_f32 v[6:7], v[6:7], v[66:67] op_sel_hi:[1,0]
	v_pk_mul_f32 v[4:5], v[4:5], v[66:67] op_sel_hi:[1,0]
	v_pk_mul_f32 v[2:3], v[2:3], v[66:67] op_sel_hi:[1,0]
	v_pk_mul_f32 v[0:1], v[0:1], v[66:67] op_sel_hi:[1,0]
	s_or_b64 s[2:3], s[2:3], s[4:5]

.LBB0_696:
	v_add3_u32 v32, s52, v151, v152
	ds_read_b128 v[140:143], v32
	ds_read_b128 v[132:135], v32 offset:512
	ds_read_b128 v[136:139], v32 offset:2048
	ds_read_b128 v[120:123], v32 offset:2560
	ds_read_b128 v[128:131], v32 offset:4096
	ds_read_b128 v[116:119], v32 offset:4608
	ds_read_b128 v[124:127], v32 offset:6144
	ds_read_b128 v[112:115], v32 offset:6656
	s_nop 0
	v_max3_f32 v32, v80, v64, v81
	v_max3_f32 v33, v65, v82, v66
	s_nop 0
	v_max3_f32 v32, v32, v83, v67
	v_max3_f32 v33, v33, v84, v68
	s_nop 0
	v_max3_f32 v32, v32, v85, v69
	v_max3_f32 v33, v33, v86, v70
	s_nop 0
	v_max3_f32 v32, v32, v87, v71
	v_max3_f32 v33, v33, v88, v72
	s_nop 0
	v_max3_f32 v32, v32, v89, v73
	v_max3_f32 v33, v33, v90, v74
	s_nop 0
	v_max3_f32 v32, v32, v91, v75
	v_max3_f32 v33, v33, v92, v76
	s_nop 0
	v_max3_f32 v32, v32, v93, v77
	v_max3_f32 v33, v33, v94, v78
	s_nop 0
	v_max3_f32 v32, v32, v95, v79
	s_nop 0
	s_nop 1
	s_nop 0
	v_max_f32_e32 v33, v33, v33
	v_max_f32_e32 v32, v32, v32
	v_max_f32_e32 v32, v32, v33
	v_mov_b32_e32 v33, v32
	s_nop 1
	v_permlane32_swap_b32_e32 v32, v33
	v_max_f32_e32 v33, v33, v33
	v_max_f32_e32 v32, v32, v32
	v_max_f32_e32 v32, v32, v33
	v_cmp_lt_f32_e32 vcc, s97, v32
	v_cmp_lg_f32_e64 s[4:5], s96, v32
	s_nop 0
	v_cndmask_b32_e64 v33, 0, 1, vcc
	v_cndmask_b32_e64 v34, 0, 1, s[4:5]
	v_cndmask_b32_e64 v33, v34, v33, s[2:3]
	v_and_b32_e32 v33, 1, v33
	v_cmp_eq_u32_e64 s[6:7], 1, v33
	v_cmp_ne_u32_e32 vcc, 0, v33
	s_cbranch_vccnz .LBB0_686
	v_xor_b32_e32 v32, 0x80000000, v154
	s_branch .LBB0_687

.LBB0_704:
	s_add_i32 s4, s18, -3
	s_min_i32 s4, s4, s43
	s_mul_hi_u32 s5, s4, 0xaaaaaaab
	s_lshr_b32 s5, s5, 1
	s_mul_i32 s5, s5, 3
	s_sub_i32 s4, s4, s5
	v_lshl_add_u32 v84, s4, 14, v168
	ds_read_b128 v[80:83], v84
	ds_read_b128 v[152:155], v84 offset:512
	ds_read_b128 v[148:151], v84 offset:2048
	ds_read_b128 v[136:139], v84 offset:2560
	ds_read_b128 v[144:147], v84 offset:4096
	ds_read_b128 v[132:135], v84 offset:4608
	ds_read_b128 v[140:143], v84 offset:6144
	ds_read_b128 v[128:131], v84 offset:6656
	s_nop 0
	v_max3_f32 v84, v48, v64, v49
	v_max3_f32 v85, v65, v50, v66
	s_nop 0
	v_max3_f32 v84, v84, v51, v67
	v_max3_f32 v85, v85, v52, v68
	s_nop 0
	v_max3_f32 v84, v84, v53, v69
	v_max3_f32 v85, v85, v54, v70
	s_nop 0
	v_max3_f32 v84, v84, v55, v71
	v_max3_f32 v85, v85, v56, v72
	s_nop 0
	v_max3_f32 v84, v84, v57, v73
	v_max3_f32 v85, v85, v58, v74
	s_nop 0
	v_max3_f32 v84, v84, v59, v75
	v_max3_f32 v85, v85, v60, v76
	s_nop 0
	v_max3_f32 v84, v84, v61, v77
	v_max3_f32 v85, v85, v62, v78
	s_nop 0
	v_max3_f32 v84, v84, v63, v79
	s_nop 0
	s_nop 1
	s_nop 0
	v_max_f32_e32 v85, v85, v85
	v_max_f32_e32 v84, v84, v84
	v_max_f32_e32 v84, v84, v85
	v_mov_b32_e32 v85, v84
	s_nop 1
	v_permlane32_swap_b32_e32 v84, v85
	v_max_f32_e32 v85, v85, v85
	v_max_f32_e32 v84, v84, v84
	v_max_f32_e32 v84, v84, v85
	v_cmp_lt_f32_e32 vcc, s97, v84
	v_cmp_lg_f32_e64 s[4:5], s96, v84
	s_nop 0
	v_cndmask_b32_e64 v85, 0, 1, vcc
	v_cndmask_b32_e64 v86, 0, 1, s[4:5]
	v_cndmask_b32_e64 v85, v86, v85, s[2:3]
	v_and_b32_e32 v85, 1, v85
	v_cmp_eq_u32_e64 s[6:7], 1, v85
	v_cmp_ne_u32_e32 vcc, 0, v85
	s_cbranch_vccz .LBB0_706
	v_cndmask_b32_e64 v32, 0, v84, s[6:7]
	v_exp_f32_e64 v34, -v32
	s_or_b64 s[4:5], s[2:3], s[4:5]
	v_add_f32_e32 v171, v171, v32
	v_pk_add_f32 v[48:49], v[48:49], v[32:33] op_sel_hi:[1,0] neg_lo:[0,1] neg_hi:[0,1]
	v_pk_add_f32 v[64:65], v[64:65], v[32:33] op_sel_hi:[1,0] neg_lo:[0,1] neg_hi:[0,1]
	v_pk_add_f32 v[50:51], v[50:51], v[32:33] op_sel_hi:[1,0] neg_lo:[0,1] neg_hi:[0,1]
	v_pk_add_f32 v[66:67], v[66:67], v[32:33] op_sel_hi:[1,0] neg_lo:[0,1] neg_hi:[0,1]
	v_pk_add_f32 v[52:53], v[52:53], v[32:33] op_sel_hi:[1,0] neg_lo:[0,1] neg_hi:[0,1]
	v_pk_add_f32 v[68:69], v[68:69], v[32:33] op_sel_hi:[1,0] neg_lo:[0,1] neg_hi:[0,1]
	v_pk_add_f32 v[54:55], v[54:55], v[32:33] op_sel_hi:[1,0] neg_lo:[0,1] neg_hi:[0,1]
	v_pk_add_f32 v[70:71], v[70:71], v[32:33] op_sel_hi:[1,0] neg_lo:[0,1] neg_hi:[0,1]
	v_pk_add_f32 v[56:57], v[56:57], v[32:33] op_sel_hi:[1,0] neg_lo:[0,1] neg_hi:[0,1]
	v_pk_add_f32 v[72:73], v[72:73], v[32:33] op_sel_hi:[1,0] neg_lo:[0,1] neg_hi:[0,1]
	v_pk_add_f32 v[58:59], v[58:59], v[32:33] op_sel_hi:[1,0] neg_lo:[0,1] neg_hi:[0,1]
	v_pk_add_f32 v[74:75], v[74:75], v[32:33] op_sel_hi:[1,0] neg_lo:[0,1] neg_hi:[0,1]
	v_pk_add_f32 v[60:61], v[60:61], v[32:33] op_sel_hi:[1,0] neg_lo:[0,1] neg_hi:[0,1]
	v_pk_add_f32 v[76:77], v[76:77], v[32:33] op_sel_hi:[1,0] neg_lo:[0,1] neg_hi:[0,1]
	v_pk_add_f32 v[62:63], v[62:63], v[32:33] op_sel_hi:[1,0] neg_lo:[0,1] neg_hi:[0,1]
	v_pk_add_f32 v[78:79], v[78:79], v[32:33] op_sel_hi:[1,0] neg_lo:[0,1] neg_hi:[0,1]
	v_xor_b32_e32 v32, 0x80000000, v171
	s_andn2_b64 s[2:3], s[2:3], exec
	s_and_b64 s[4:5], s[4:5], exec
	v_mul_f32_e32 v165, v165, v34
	v_pk_mul_f32 v[14:15], v[14:15], v[34:35] op_sel_hi:[1,0]
	v_pk_mul_f32 v[12:13], v[12:13], v[34:35] op_sel_hi:[1,0]
	v_pk_mul_f32 v[10:11], v[10:11], v[34:35] op_sel_hi:[1,0]
	v_pk_mul_f32 v[8:9], v[8:9], v[34:35] op_sel_hi:[1,0]
	v_pk_mul_f32 v[6:7], v[6:7], v[34:35] op_sel_hi:[1,0]
	v_pk_mul_f32 v[4:5], v[4:5], v[34:35] op_sel_hi:[1,0]
	v_pk_mul_f32 v[2:3], v[2:3], v[34:35] op_sel_hi:[1,0]
	v_pk_mul_f32 v[0:1], v[0:1], v[34:35] op_sel_hi:[1,0]
	v_pk_mul_f32 v[30:31], v[30:31], v[34:35] op_sel_hi:[1,0]
	v_pk_mul_f32 v[28:29], v[28:29], v[34:35] op_sel_hi:[1,0]
	v_pk_mul_f32 v[26:27], v[26:27], v[34:35] op_sel_hi:[1,0]
	v_pk_mul_f32 v[24:25], v[24:25], v[34:35] op_sel_hi:[1,0]
	v_pk_mul_f32 v[22:23], v[22:23], v[34:35] op_sel_hi:[1,0]
	v_pk_mul_f32 v[20:21], v[20:21], v[34:35] op_sel_hi:[1,0]
	v_pk_mul_f32 v[18:19], v[18:19], v[34:35] op_sel_hi:[1,0]
	v_pk_mul_f32 v[16:17], v[16:17], v[34:35] op_sel_hi:[1,0]
	v_mov_b32_e32 v33, v32
	v_mov_b32_e32 v34, v32
	v_mov_b32_e32 v35, v32
	v_mov_b32_e32 v36, v32
	v_mov_b32_e32 v37, v32
	v_mov_b32_e32 v38, v32
	v_mov_b32_e32 v39, v32
	v_mov_b32_e32 v40, v32
	v_mov_b32_e32 v41, v32
	v_mov_b32_e32 v42, v32
	v_mov_b32_e32 v43, v32
	v_mov_b32_e32 v44, v32
	v_mov_b32_e32 v45, v32
	v_mov_b32_e32 v46, v32
	v_mov_b32_e32 v47, v32
	s_or_b64 s[2:3], s[2:3], s[4:5]

.LBB0_709:
	v_add3_u32 v48, s22, v166, v167
	ds_read_b128 v[64:67], v48
	ds_read_b128 v[152:155], v48 offset:512
	ds_read_b128 v[140:143], v48 offset:2048
	ds_read_b128 v[132:135], v48 offset:2560
	ds_read_b128 v[144:147], v48 offset:4096
	ds_read_b128 v[136:139], v48 offset:4608
	ds_read_b128 v[148:151], v48 offset:6144
	ds_read_b128 v[128:131], v48 offset:6656
	s_nop 0
	v_max3_f32 v48, v96, v80, v97
	v_max3_f32 v49, v81, v98, v82
	s_nop 0
	v_max3_f32 v48, v48, v99, v83
	v_max3_f32 v49, v49, v100, v84
	s_nop 0
	v_max3_f32 v48, v48, v101, v85
	v_max3_f32 v49, v49, v102, v86
	s_nop 0
	v_max3_f32 v48, v48, v103, v87
	v_max3_f32 v49, v49, v104, v88
	s_nop 0
	v_max3_f32 v48, v48, v105, v89
	v_max3_f32 v49, v49, v106, v90
	s_nop 0
	v_max3_f32 v48, v48, v107, v91
	v_max3_f32 v49, v49, v108, v92
	s_nop 0
	v_max3_f32 v48, v48, v109, v93
	v_max3_f32 v49, v49, v110, v94
	s_nop 0
	v_max3_f32 v48, v48, v111, v95
	s_nop 0
	s_nop 1
	s_nop 0
	v_max_f32_e32 v49, v49, v49
	v_max_f32_e32 v48, v48, v48
	v_max_f32_e32 v48, v48, v49
	v_mov_b32_e32 v49, v48
	s_nop 1
	v_permlane32_swap_b32_e32 v48, v49
	v_max_f32_e32 v49, v49, v49
	v_max_f32_e32 v48, v48, v48
	v_max_f32_e32 v48, v48, v49
	v_cmp_lt_f32_e32 vcc, s97, v48
	v_cmp_lg_f32_e64 s[4:5], s96, v48
	s_nop 0
	v_cndmask_b32_e64 v49, 0, 1, vcc
	v_cndmask_b32_e64 v50, 0, 1, s[4:5]
	v_cndmask_b32_e64 v49, v50, v49, s[2:3]
	v_and_b32_e32 v49, 1, v49
	v_cmp_eq_u32_e64 s[6:7], 1, v49
	v_cmp_ne_u32_e32 vcc, 0, v49
	s_cbranch_vccz .LBB0_700
	v_cndmask_b32_e64 v32, 0, v48, s[6:7]
	v_exp_f32_e64 v34, -v32
	s_or_b64 s[4:5], s[2:3], s[4:5]
	v_add_f32_e32 v171, v171, v32
	v_pk_add_f32 v[96:97], v[96:97], v[32:33] op_sel_hi:[1,0] neg_lo:[0,1] neg_hi:[0,1]
	v_pk_add_f32 v[80:81], v[80:81], v[32:33] op_sel_hi:[1,0] neg_lo:[0,1] neg_hi:[0,1]
	v_pk_add_f32 v[98:99], v[98:99], v[32:33] op_sel_hi:[1,0] neg_lo:[0,1] neg_hi:[0,1]
	v_pk_add_f32 v[82:83], v[82:83], v[32:33] op_sel_hi:[1,0] neg_lo:[0,1] neg_hi:[0,1]
	v_pk_add_f32 v[100:101], v[100:101], v[32:33] op_sel_hi:[1,0] neg_lo:[0,1] neg_hi:[0,1]
	v_pk_add_f32 v[84:85], v[84:85], v[32:33] op_sel_hi:[1,0] neg_lo:[0,1] neg_hi:[0,1]
	v_pk_add_f32 v[102:103], v[102:103], v[32:33] op_sel_hi:[1,0] neg_lo:[0,1] neg_hi:[0,1]
	v_pk_add_f32 v[86:87], v[86:87], v[32:33] op_sel_hi:[1,0] neg_lo:[0,1] neg_hi:[0,1]
	v_pk_add_f32 v[104:105], v[104:105], v[32:33] op_sel_hi:[1,0] neg_lo:[0,1] neg_hi:[0,1]
	v_pk_add_f32 v[88:89], v[88:89], v[32:33] op_sel_hi:[1,0] neg_lo:[0,1] neg_hi:[0,1]
	v_pk_add_f32 v[106:107], v[106:107], v[32:33] op_sel_hi:[1,0] neg_lo:[0,1] neg_hi:[0,1]
	v_pk_add_f32 v[90:91], v[90:91], v[32:33] op_sel_hi:[1,0] neg_lo:[0,1] neg_hi:[0,1]
	v_pk_add_f32 v[108:109], v[108:109], v[32:33] op_sel_hi:[1,0] neg_lo:[0,1] neg_hi:[0,1]
	v_pk_add_f32 v[92:93], v[92:93], v[32:33] op_sel_hi:[1,0] neg_lo:[0,1] neg_hi:[0,1]
	v_pk_add_f32 v[110:111], v[110:111], v[32:33] op_sel_hi:[1,0] neg_lo:[0,1] neg_hi:[0,1]
	v_pk_add_f32 v[94:95], v[94:95], v[32:33] op_sel_hi:[1,0] neg_lo:[0,1] neg_hi:[0,1]
	v_xor_b32_e32 v32, 0x80000000, v171
	s_andn2_b64 s[2:3], s[2:3], exec
	s_and_b64 s[4:5], s[4:5], exec
	v_mul_f32_e32 v165, v165, v34
	v_pk_mul_f32 v[14:15], v[14:15], v[34:35] op_sel_hi:[1,0]
	v_pk_mul_f32 v[12:13], v[12:13], v[34:35] op_sel_hi:[1,0]
	v_pk_mul_f32 v[10:11], v[10:11], v[34:35] op_sel_hi:[1,0]
	v_pk_mul_f32 v[8:9], v[8:9], v[34:35] op_sel_hi:[1,0]
	v_pk_mul_f32 v[6:7], v[6:7], v[34:35] op_sel_hi:[1,0]
	v_pk_mul_f32 v[4:5], v[4:5], v[34:35] op_sel_hi:[1,0]
	v_pk_mul_f32 v[2:3], v[2:3], v[34:35] op_sel_hi:[1,0]
	v_pk_mul_f32 v[0:1], v[0:1], v[34:35] op_sel_hi:[1,0]
	v_pk_mul_f32 v[30:31], v[30:31], v[34:35] op_sel_hi:[1,0]
	v_pk_mul_f32 v[28:29], v[28:29], v[34:35] op_sel_hi:[1,0]
	v_pk_mul_f32 v[26:27], v[26:27], v[34:35] op_sel_hi:[1,0]
	v_pk_mul_f32 v[24:25], v[24:25], v[34:35] op_sel_hi:[1,0]
	v_pk_mul_f32 v[22:23], v[22:23], v[34:35] op_sel_hi:[1,0]
	v_pk_mul_f32 v[20:21], v[20:21], v[34:35] op_sel_hi:[1,0]
	v_pk_mul_f32 v[18:19], v[18:19], v[34:35] op_sel_hi:[1,0]
	v_pk_mul_f32 v[16:17], v[16:17], v[34:35] op_sel_hi:[1,0]
	v_mov_b32_e32 v33, v32
	v_mov_b32_e32 v34, v32
	v_mov_b32_e32 v35, v32
	v_mov_b32_e32 v36, v32
	v_mov_b32_e32 v37, v32
	v_mov_b32_e32 v38, v32
	v_mov_b32_e32 v39, v32
	v_mov_b32_e32 v40, v32
	v_mov_b32_e32 v41, v32
	v_mov_b32_e32 v42, v32
	v_mov_b32_e32 v43, v32
	v_mov_b32_e32 v44, v32
	v_mov_b32_e32 v45, v32
	v_mov_b32_e32 v46, v32
	v_mov_b32_e32 v47, v32
	s_or_b64 s[2:3], s[2:3], s[4:5]
	s_branch .LBB0_700

.LBB0_719:
	s_add_i32 s4, s19, -3
	s_min_u32 s4, s4, s22
	s_mul_hi_u32 s5, s4, 0x55555556
	s_mul_i32 s5, s5, 3
	s_sub_i32 s4, s4, s5
	s_mulk_i32 s4, 0x5000
	v_add_u32_e32 v84, s4, v194
	ds_read_b128 v[80:83], v84
	ds_read_b128 v[176:179], v84 offset:512
	ds_read_b128 v[168:171], v84 offset:2048
	ds_read_b128 v[152:155], v84 offset:2560
	ds_read_b128 v[172:175], v84 offset:4096
	ds_read_b128 v[148:151], v84 offset:4608
	ds_read_b128 v[164:167], v84 offset:6144
	ds_read_b128 v[144:147], v84 offset:6656
	ds_read_b128 v[160:163], v84 offset:8192
	ds_read_b128 v[140:143], v84 offset:8704
	ds_read_b128 v[156:159], v84 offset:10240
	ds_read_b128 v[136:139], v84 offset:10752
	s_nop 0
	v_max3_f32 v84, v48, v64, v49
	v_max3_f32 v85, v65, v50, v66
	s_nop 0
	v_max3_f32 v84, v84, v51, v67
	v_max3_f32 v85, v85, v52, v68
	s_nop 0
	v_max3_f32 v84, v84, v53, v69
	v_max3_f32 v85, v85, v54, v70
	s_nop 0
	v_max3_f32 v84, v84, v55, v71
	v_max3_f32 v85, v85, v56, v72
	s_nop 0
	v_max3_f32 v84, v84, v57, v73
	v_max3_f32 v85, v85, v58, v74
	s_nop 0
	v_max3_f32 v84, v84, v59, v75
	v_max3_f32 v85, v85, v60, v76
	s_nop 0
	v_max3_f32 v84, v84, v61, v77
	v_max3_f32 v85, v85, v62, v78
	s_nop 0
	v_max3_f32 v84, v84, v63, v79
	s_nop 0
	s_nop 1
	s_nop 0
	v_max_f32_e32 v85, v85, v85
	v_max_f32_e32 v84, v84, v84
	v_max_f32_e32 v84, v84, v85
	v_mov_b32_e32 v85, v84
	s_nop 1
	v_permlane32_swap_b32_e32 v84, v85
	v_max_f32_e32 v85, v85, v85
	v_max_f32_e32 v84, v84, v84
	v_max_f32_e32 v84, v84, v85
	v_cmp_lt_f32_e32 vcc, s97, v84
	v_cmp_lg_f32_e64 s[4:5], s96, v84
	s_nop 0
	v_cndmask_b32_e64 v85, 0, 1, vcc
	v_cndmask_b32_e64 v86, 0, 1, s[4:5]
	v_cndmask_b32_e64 v85, v86, v85, s[2:3]
	v_and_b32_e32 v85, 1, v85
	v_cmp_eq_u32_e64 s[6:7], 1, v85
	v_cmp_ne_u32_e32 vcc, 0, v85
	s_cbranch_vccz .LBB0_721
	v_cndmask_b32_e64 v32, 0, v84, s[6:7]
	v_exp_f32_e64 v34, -v32
	s_or_b64 s[4:5], s[2:3], s[4:5]
	v_add_f32_e32 v197, v197, v32
	v_pk_add_f32 v[48:49], v[48:49], v[32:33] op_sel_hi:[1,0] neg_lo:[0,1] neg_hi:[0,1]
	v_pk_add_f32 v[64:65], v[64:65], v[32:33] op_sel_hi:[1,0] neg_lo:[0,1] neg_hi:[0,1]
	v_pk_add_f32 v[50:51], v[50:51], v[32:33] op_sel_hi:[1,0] neg_lo:[0,1] neg_hi:[0,1]
	v_pk_add_f32 v[66:67], v[66:67], v[32:33] op_sel_hi:[1,0] neg_lo:[0,1] neg_hi:[0,1]
	v_pk_add_f32 v[52:53], v[52:53], v[32:33] op_sel_hi:[1,0] neg_lo:[0,1] neg_hi:[0,1]
	v_pk_add_f32 v[68:69], v[68:69], v[32:33] op_sel_hi:[1,0] neg_lo:[0,1] neg_hi:[0,1]
	v_pk_add_f32 v[54:55], v[54:55], v[32:33] op_sel_hi:[1,0] neg_lo:[0,1] neg_hi:[0,1]
	v_pk_add_f32 v[70:71], v[70:71], v[32:33] op_sel_hi:[1,0] neg_lo:[0,1] neg_hi:[0,1]
	v_pk_add_f32 v[56:57], v[56:57], v[32:33] op_sel_hi:[1,0] neg_lo:[0,1] neg_hi:[0,1]
	v_pk_add_f32 v[72:73], v[72:73], v[32:33] op_sel_hi:[1,0] neg_lo:[0,1] neg_hi:[0,1]
	v_pk_add_f32 v[58:59], v[58:59], v[32:33] op_sel_hi:[1,0] neg_lo:[0,1] neg_hi:[0,1]
	v_pk_add_f32 v[74:75], v[74:75], v[32:33] op_sel_hi:[1,0] neg_lo:[0,1] neg_hi:[0,1]
	v_pk_add_f32 v[60:61], v[60:61], v[32:33] op_sel_hi:[1,0] neg_lo:[0,1] neg_hi:[0,1]
	v_pk_add_f32 v[76:77], v[76:77], v[32:33] op_sel_hi:[1,0] neg_lo:[0,1] neg_hi:[0,1]
	v_pk_add_f32 v[62:63], v[62:63], v[32:33] op_sel_hi:[1,0] neg_lo:[0,1] neg_hi:[0,1]
	v_pk_add_f32 v[78:79], v[78:79], v[32:33] op_sel_hi:[1,0] neg_lo:[0,1] neg_hi:[0,1]
	v_xor_b32_e32 v32, 0x80000000, v197
	s_andn2_b64 s[2:3], s[2:3], exec
	s_and_b64 s[4:5], s[4:5], exec
	v_mul_f32_e32 v198, v198, v34
	v_pk_mul_f32 v[30:31], v[30:31], v[34:35] op_sel_hi:[1,0]
	v_pk_mul_f32 v[28:29], v[28:29], v[34:35] op_sel_hi:[1,0]
	v_pk_mul_f32 v[26:27], v[26:27], v[34:35] op_sel_hi:[1,0]
	v_pk_mul_f32 v[24:25], v[24:25], v[34:35] op_sel_hi:[1,0]
	v_pk_mul_f32 v[22:23], v[22:23], v[34:35] op_sel_hi:[1,0]
	v_pk_mul_f32 v[20:21], v[20:21], v[34:35] op_sel_hi:[1,0]
	v_pk_mul_f32 v[18:19], v[18:19], v[34:35] op_sel_hi:[1,0]
	v_pk_mul_f32 v[16:17], v[16:17], v[34:35] op_sel_hi:[1,0]
	v_pk_mul_f32 v[14:15], v[14:15], v[34:35] op_sel_hi:[1,0]
	v_pk_mul_f32 v[12:13], v[12:13], v[34:35] op_sel_hi:[1,0]
	v_pk_mul_f32 v[10:11], v[10:11], v[34:35] op_sel_hi:[1,0]
	v_pk_mul_f32 v[8:9], v[8:9], v[34:35] op_sel_hi:[1,0]
	v_pk_mul_f32 v[6:7], v[6:7], v[34:35] op_sel_hi:[1,0]
	v_pk_mul_f32 v[4:5], v[4:5], v[34:35] op_sel_hi:[1,0]
	v_pk_mul_f32 v[2:3], v[2:3], v[34:35] op_sel_hi:[1,0]
	v_pk_mul_f32 v[0:1], v[0:1], v[34:35] op_sel_hi:[1,0]
	v_mov_b32_e32 v33, v32
	v_mov_b32_e32 v34, v32
	v_mov_b32_e32 v35, v32
	v_mov_b32_e32 v36, v32
	v_mov_b32_e32 v37, v32
	v_mov_b32_e32 v38, v32
	v_mov_b32_e32 v39, v32
	v_mov_b32_e32 v40, v32
	v_mov_b32_e32 v41, v32
	v_mov_b32_e32 v42, v32
	v_mov_b32_e32 v43, v32
	v_mov_b32_e32 v44, v32
	v_mov_b32_e32 v45, v32
	v_mov_b32_e32 v46, v32
	v_mov_b32_e32 v47, v32
	s_or_b64 s[2:3], s[2:3], s[4:5]

.LBB0_724:
	v_add3_u32 v48, s43, v192, v193
	ds_read_b128 v[64:67], v48
	ds_read_b128 v[176:179], v48 offset:512
	ds_read_b128 v[168:171], v48 offset:2048
	ds_read_b128 v[152:155], v48 offset:2560
	ds_read_b128 v[172:175], v48 offset:4096
	ds_read_b128 v[148:151], v48 offset:4608
	ds_read_b128 v[164:167], v48 offset:6144
	ds_read_b128 v[144:147], v48 offset:6656
	ds_read_b128 v[160:163], v48 offset:8192
	ds_read_b128 v[140:143], v48 offset:8704
	ds_read_b128 v[156:159], v48 offset:10240
	ds_read_b128 v[136:139], v48 offset:10752
	s_nop 0
	v_max3_f32 v48, v96, v80, v97
	v_max3_f32 v49, v81, v98, v82
	s_nop 0
	v_max3_f32 v48, v48, v99, v83
	v_max3_f32 v49, v49, v100, v84
	s_nop 0
	v_max3_f32 v48, v48, v101, v85
	v_max3_f32 v49, v49, v102, v86
	s_nop 0
	v_max3_f32 v48, v48, v103, v87
	v_max3_f32 v49, v49, v104, v88
	s_nop 0
	v_max3_f32 v48, v48, v105, v89
	v_max3_f32 v49, v49, v106, v90
	s_nop 0
	v_max3_f32 v48, v48, v107, v91
	v_max3_f32 v49, v49, v108, v92
	s_nop 0
	v_max3_f32 v48, v48, v109, v93
	v_max3_f32 v49, v49, v110, v94
	s_nop 0
	v_max3_f32 v48, v48, v111, v95
	s_nop 0
	s_nop 1
	s_nop 0
	v_max_f32_e32 v49, v49, v49
	v_max_f32_e32 v48, v48, v48
	v_max_f32_e32 v48, v48, v49
	v_mov_b32_e32 v49, v48
	s_nop 1
	v_permlane32_swap_b32_e32 v48, v49
	v_max_f32_e32 v49, v49, v49
	v_max_f32_e32 v48, v48, v48
	v_max_f32_e32 v48, v48, v49
	v_cmp_lt_f32_e32 vcc, s97, v48
	v_cmp_lg_f32_e64 s[4:5], s96, v48
	s_nop 0
	v_cndmask_b32_e64 v49, 0, 1, vcc
	v_cndmask_b32_e64 v50, 0, 1, s[4:5]
	v_cndmask_b32_e64 v49, v50, v49, s[2:3]
	v_and_b32_e32 v49, 1, v49
	v_cmp_eq_u32_e64 s[6:7], 1, v49
	v_cmp_ne_u32_e32 vcc, 0, v49
	s_cbranch_vccz .LBB0_715
	v_cndmask_b32_e64 v32, 0, v48, s[6:7]
	v_exp_f32_e64 v34, -v32
	s_or_b64 s[4:5], s[2:3], s[4:5]
	v_add_f32_e32 v197, v197, v32
	v_pk_add_f32 v[96:97], v[96:97], v[32:33] op_sel_hi:[1,0] neg_lo:[0,1] neg_hi:[0,1]
	v_pk_add_f32 v[80:81], v[80:81], v[32:33] op_sel_hi:[1,0] neg_lo:[0,1] neg_hi:[0,1]
	v_pk_add_f32 v[98:99], v[98:99], v[32:33] op_sel_hi:[1,0] neg_lo:[0,1] neg_hi:[0,1]
	v_pk_add_f32 v[82:83], v[82:83], v[32:33] op_sel_hi:[1,0] neg_lo:[0,1] neg_hi:[0,1]
	v_pk_add_f32 v[100:101], v[100:101], v[32:33] op_sel_hi:[1,0] neg_lo:[0,1] neg_hi:[0,1]
	v_pk_add_f32 v[84:85], v[84:85], v[32:33] op_sel_hi:[1,0] neg_lo:[0,1] neg_hi:[0,1]
	v_pk_add_f32 v[102:103], v[102:103], v[32:33] op_sel_hi:[1,0] neg_lo:[0,1] neg_hi:[0,1]
	v_pk_add_f32 v[86:87], v[86:87], v[32:33] op_sel_hi:[1,0] neg_lo:[0,1] neg_hi:[0,1]
	v_pk_add_f32 v[104:105], v[104:105], v[32:33] op_sel_hi:[1,0] neg_lo:[0,1] neg_hi:[0,1]
	v_pk_add_f32 v[88:89], v[88:89], v[32:33] op_sel_hi:[1,0] neg_lo:[0,1] neg_hi:[0,1]
	v_pk_add_f32 v[106:107], v[106:107], v[32:33] op_sel_hi:[1,0] neg_lo:[0,1] neg_hi:[0,1]
	v_pk_add_f32 v[90:91], v[90:91], v[32:33] op_sel_hi:[1,0] neg_lo:[0,1] neg_hi:[0,1]
	v_pk_add_f32 v[108:109], v[108:109], v[32:33] op_sel_hi:[1,0] neg_lo:[0,1] neg_hi:[0,1]
	v_pk_add_f32 v[92:93], v[92:93], v[32:33] op_sel_hi:[1,0] neg_lo:[0,1] neg_hi:[0,1]
	v_pk_add_f32 v[110:111], v[110:111], v[32:33] op_sel_hi:[1,0] neg_lo:[0,1] neg_hi:[0,1]
	v_pk_add_f32 v[94:95], v[94:95], v[32:33] op_sel_hi:[1,0] neg_lo:[0,1] neg_hi:[0,1]
	v_xor_b32_e32 v32, 0x80000000, v197
	s_andn2_b64 s[2:3], s[2:3], exec
	s_and_b64 s[4:5], s[4:5], exec
	v_mul_f32_e32 v198, v198, v34
	v_pk_mul_f32 v[30:31], v[30:31], v[34:35] op_sel_hi:[1,0]
	v_pk_mul_f32 v[28:29], v[28:29], v[34:35] op_sel_hi:[1,0]
	v_pk_mul_f32 v[26:27], v[26:27], v[34:35] op_sel_hi:[1,0]
	v_pk_mul_f32 v[24:25], v[24:25], v[34:35] op_sel_hi:[1,0]
	v_pk_mul_f32 v[22:23], v[22:23], v[34:35] op_sel_hi:[1,0]
	v_pk_mul_f32 v[20:21], v[20:21], v[34:35] op_sel_hi:[1,0]
	v_pk_mul_f32 v[18:19], v[18:19], v[34:35] op_sel_hi:[1,0]
	v_pk_mul_f32 v[16:17], v[16:17], v[34:35] op_sel_hi:[1,0]
	v_pk_mul_f32 v[14:15], v[14:15], v[34:35] op_sel_hi:[1,0]
	v_pk_mul_f32 v[12:13], v[12:13], v[34:35] op_sel_hi:[1,0]
	v_pk_mul_f32 v[10:11], v[10:11], v[34:35] op_sel_hi:[1,0]
	v_pk_mul_f32 v[8:9], v[8:9], v[34:35] op_sel_hi:[1,0]
	v_pk_mul_f32 v[6:7], v[6:7], v[34:35] op_sel_hi:[1,0]
	v_pk_mul_f32 v[4:5], v[4:5], v[34:35] op_sel_hi:[1,0]
	v_pk_mul_f32 v[2:3], v[2:3], v[34:35] op_sel_hi:[1,0]
	v_pk_mul_f32 v[0:1], v[0:1], v[34:35] op_sel_hi:[1,0]
	v_mov_b32_e32 v33, v32
	v_mov_b32_e32 v34, v32
	v_mov_b32_e32 v35, v32
	v_mov_b32_e32 v36, v32
	v_mov_b32_e32 v37, v32
	v_mov_b32_e32 v38, v32
	v_mov_b32_e32 v39, v32
	v_mov_b32_e32 v40, v32
	v_mov_b32_e32 v41, v32
	v_mov_b32_e32 v42, v32
	v_mov_b32_e32 v43, v32
	v_mov_b32_e32 v44, v32
	v_mov_b32_e32 v45, v32
	v_mov_b32_e32 v46, v32
	v_mov_b32_e32 v47, v32
	s_or_b64 s[2:3], s[2:3], s[4:5]
	s_branch .LBB0_715

.LBB0_734:
	s_add_i32 s4, s21, -3
	s_min_u32 s4, s4, s40
	s_mul_hi_u32 s5, s4, 0x55555556
	s_mul_i32 s5, s5, 3
	s_sub_i32 s4, s4, s5
	s_mulk_i32 s4, 0x3000
	v_add_u32_e32 v88, s4, v134
	ds_read_b128 v[84:87], v88
	ds_read_b128 v[124:127], v88 offset:512
	ds_read_b128 v[80:83], v88 offset:2048
	ds_read_b128 v[120:123], v88 offset:2560
	s_nop 0
	v_max3_f32 v88, v48, v64, v49
	v_max3_f32 v89, v65, v50, v66
	s_nop 0
	v_max3_f32 v88, v88, v51, v67
	v_max3_f32 v89, v89, v52, v68
	s_nop 0
	v_max3_f32 v88, v88, v53, v69
	v_max3_f32 v89, v89, v54, v70
	s_nop 0
	v_max3_f32 v88, v88, v55, v71
	v_max3_f32 v89, v89, v56, v72
	s_nop 0
	v_max3_f32 v88, v88, v57, v73
	v_max3_f32 v89, v89, v58, v74
	s_nop 0
	v_max3_f32 v88, v88, v59, v75
	v_max3_f32 v89, v89, v60, v76
	s_nop 0
	v_max3_f32 v88, v88, v61, v77
	v_max3_f32 v89, v89, v62, v78
	s_nop 0
	v_max3_f32 v88, v88, v63, v79
	s_nop 0
	s_nop 1
	s_nop 0
	v_max_f32_e32 v89, v89, v89
	v_max_f32_e32 v88, v88, v88
	v_max_f32_e32 v88, v88, v89
	v_mov_b32_e32 v89, v88
	s_nop 1
	v_permlane32_swap_b32_e32 v88, v89
	v_max_f32_e32 v89, v89, v89
	v_max_f32_e32 v88, v88, v88
	v_max_f32_e32 v88, v88, v89
	v_cmp_lt_f32_e32 vcc, s97, v88
	v_cmp_lg_f32_e64 s[4:5], s96, v88
	s_nop 0
	v_cndmask_b32_e64 v89, 0, 1, vcc
	v_cndmask_b32_e64 v90, 0, 1, s[4:5]
	v_cndmask_b32_e64 v89, v90, v89, s[2:3]
	v_and_b32_e32 v89, 1, v89
	v_cmp_eq_u32_e64 s[6:7], 1, v89
	v_cmp_ne_u32_e32 vcc, 0, v89
	s_cbranch_vccz .LBB0_736
	v_cndmask_b32_e64 v32, 0, v88, s[6:7]
	v_exp_f32_e64 v34, -v32
	s_or_b64 s[4:5], s[2:3], s[4:5]
	v_add_f32_e32 v137, v137, v32
	v_pk_add_f32 v[48:49], v[48:49], v[32:33] op_sel_hi:[1,0] neg_lo:[0,1] neg_hi:[0,1]
	v_pk_add_f32 v[64:65], v[64:65], v[32:33] op_sel_hi:[1,0] neg_lo:[0,1] neg_hi:[0,1]
	v_pk_add_f32 v[50:51], v[50:51], v[32:33] op_sel_hi:[1,0] neg_lo:[0,1] neg_hi:[0,1]
	v_pk_add_f32 v[66:67], v[66:67], v[32:33] op_sel_hi:[1,0] neg_lo:[0,1] neg_hi:[0,1]
	v_pk_add_f32 v[52:53], v[52:53], v[32:33] op_sel_hi:[1,0] neg_lo:[0,1] neg_hi:[0,1]
	v_pk_add_f32 v[68:69], v[68:69], v[32:33] op_sel_hi:[1,0] neg_lo:[0,1] neg_hi:[0,1]
	v_pk_add_f32 v[54:55], v[54:55], v[32:33] op_sel_hi:[1,0] neg_lo:[0,1] neg_hi:[0,1]
	v_pk_add_f32 v[70:71], v[70:71], v[32:33] op_sel_hi:[1,0] neg_lo:[0,1] neg_hi:[0,1]
	v_pk_add_f32 v[56:57], v[56:57], v[32:33] op_sel_hi:[1,0] neg_lo:[0,1] neg_hi:[0,1]
	v_pk_add_f32 v[72:73], v[72:73], v[32:33] op_sel_hi:[1,0] neg_lo:[0,1] neg_hi:[0,1]
	v_pk_add_f32 v[58:59], v[58:59], v[32:33] op_sel_hi:[1,0] neg_lo:[0,1] neg_hi:[0,1]
	v_pk_add_f32 v[74:75], v[74:75], v[32:33] op_sel_hi:[1,0] neg_lo:[0,1] neg_hi:[0,1]
	v_pk_add_f32 v[60:61], v[60:61], v[32:33] op_sel_hi:[1,0] neg_lo:[0,1] neg_hi:[0,1]
	v_pk_add_f32 v[76:77], v[76:77], v[32:33] op_sel_hi:[1,0] neg_lo:[0,1] neg_hi:[0,1]
	v_pk_add_f32 v[62:63], v[62:63], v[32:33] op_sel_hi:[1,0] neg_lo:[0,1] neg_hi:[0,1]
	v_pk_add_f32 v[78:79], v[78:79], v[32:33] op_sel_hi:[1,0] neg_lo:[0,1] neg_hi:[0,1]
	v_xor_b32_e32 v32, 0x80000000, v137
	s_andn2_b64 s[2:3], s[2:3], exec
	s_and_b64 s[4:5], s[4:5], exec
	v_mul_f32_e32 v138, v138, v34
	v_pk_mul_f32 v[30:31], v[30:31], v[34:35] op_sel_hi:[1,0]
	v_pk_mul_f32 v[28:29], v[28:29], v[34:35] op_sel_hi:[1,0]
	v_pk_mul_f32 v[26:27], v[26:27], v[34:35] op_sel_hi:[1,0]
	v_pk_mul_f32 v[24:25], v[24:25], v[34:35] op_sel_hi:[1,0]
	v_pk_mul_f32 v[22:23], v[22:23], v[34:35] op_sel_hi:[1,0]
	v_pk_mul_f32 v[20:21], v[20:21], v[34:35] op_sel_hi:[1,0]
	v_pk_mul_f32 v[18:19], v[18:19], v[34:35] op_sel_hi:[1,0]
	v_pk_mul_f32 v[16:17], v[16:17], v[34:35] op_sel_hi:[1,0]
	v_pk_mul_f32 v[14:15], v[14:15], v[34:35] op_sel_hi:[1,0]
	v_pk_mul_f32 v[12:13], v[12:13], v[34:35] op_sel_hi:[1,0]
	v_pk_mul_f32 v[10:11], v[10:11], v[34:35] op_sel_hi:[1,0]
	v_pk_mul_f32 v[8:9], v[8:9], v[34:35] op_sel_hi:[1,0]
	v_pk_mul_f32 v[6:7], v[6:7], v[34:35] op_sel_hi:[1,0]
	v_pk_mul_f32 v[4:5], v[4:5], v[34:35] op_sel_hi:[1,0]
	v_pk_mul_f32 v[2:3], v[2:3], v[34:35] op_sel_hi:[1,0]
	v_pk_mul_f32 v[0:1], v[0:1], v[34:35] op_sel_hi:[1,0]
	v_mov_b32_e32 v33, v32
	v_mov_b32_e32 v34, v32
	v_mov_b32_e32 v35, v32
	v_mov_b32_e32 v36, v32
	v_mov_b32_e32 v37, v32
	v_mov_b32_e32 v38, v32
	v_mov_b32_e32 v39, v32
	v_mov_b32_e32 v40, v32
	v_mov_b32_e32 v41, v32
	v_mov_b32_e32 v42, v32
	v_mov_b32_e32 v43, v32
	v_mov_b32_e32 v44, v32
	v_mov_b32_e32 v45, v32
	v_mov_b32_e32 v46, v32
	v_mov_b32_e32 v47, v32
	s_or_b64 s[2:3], s[2:3], s[4:5]

.LBB0_739:
	v_add3_u32 v48, s47, v132, v133
	ds_read_b128 v[68:71], v48
	ds_read_b128 v[124:127], v48 offset:512
	ds_read_b128 v[64:67], v48 offset:2048
	ds_read_b128 v[120:123], v48 offset:2560
	s_nop 0
	v_max3_f32 v48, v96, v80, v97
	v_max3_f32 v49, v81, v98, v82
	s_nop 0
	v_max3_f32 v48, v48, v99, v83
	v_max3_f32 v49, v49, v100, v84
	s_nop 0
	v_max3_f32 v48, v48, v101, v85
	v_max3_f32 v49, v49, v102, v86
	s_nop 0
	v_max3_f32 v48, v48, v103, v87
	v_max3_f32 v49, v49, v104, v88
	s_nop 0
	v_max3_f32 v48, v48, v105, v89
	v_max3_f32 v49, v49, v106, v90
	s_nop 0
	v_max3_f32 v48, v48, v107, v91
	v_max3_f32 v49, v49, v108, v92
	s_nop 0
	v_max3_f32 v48, v48, v109, v93
	v_max3_f32 v49, v49, v110, v94
	s_nop 0
	v_max3_f32 v48, v48, v111, v95
	s_nop 0
	s_nop 1
	s_nop 0
	v_max_f32_e32 v49, v49, v49
	v_max_f32_e32 v48, v48, v48
	v_max_f32_e32 v48, v48, v49
	v_mov_b32_e32 v49, v48
	s_nop 1
	v_permlane32_swap_b32_e32 v48, v49
	v_max_f32_e32 v49, v49, v49
	v_max_f32_e32 v48, v48, v48
	v_max_f32_e32 v48, v48, v49
	v_cmp_lt_f32_e32 vcc, s97, v48
	v_cmp_lg_f32_e64 s[4:5], s96, v48
	s_nop 0
	v_cndmask_b32_e64 v49, 0, 1, vcc
	v_cndmask_b32_e64 v50, 0, 1, s[4:5]
	v_cndmask_b32_e64 v49, v50, v49, s[2:3]
	v_and_b32_e32 v49, 1, v49
	v_cmp_eq_u32_e64 s[6:7], 1, v49
	v_cmp_ne_u32_e32 vcc, 0, v49
	s_cbranch_vccz .LBB0_730
	v_cndmask_b32_e64 v32, 0, v48, s[6:7]
	v_exp_f32_e64 v34, -v32
	s_or_b64 s[4:5], s[2:3], s[4:5]
	v_add_f32_e32 v137, v137, v32
	v_pk_add_f32 v[96:97], v[96:97], v[32:33] op_sel_hi:[1,0] neg_lo:[0,1] neg_hi:[0,1]
	v_pk_add_f32 v[80:81], v[80:81], v[32:33] op_sel_hi:[1,0] neg_lo:[0,1] neg_hi:[0,1]
	v_pk_add_f32 v[98:99], v[98:99], v[32:33] op_sel_hi:[1,0] neg_lo:[0,1] neg_hi:[0,1]
	v_pk_add_f32 v[82:83], v[82:83], v[32:33] op_sel_hi:[1,0] neg_lo:[0,1] neg_hi:[0,1]
	v_pk_add_f32 v[100:101], v[100:101], v[32:33] op_sel_hi:[1,0] neg_lo:[0,1] neg_hi:[0,1]
	v_pk_add_f32 v[84:85], v[84:85], v[32:33] op_sel_hi:[1,0] neg_lo:[0,1] neg_hi:[0,1]
	v_pk_add_f32 v[102:103], v[102:103], v[32:33] op_sel_hi:[1,0] neg_lo:[0,1] neg_hi:[0,1]
	v_pk_add_f32 v[86:87], v[86:87], v[32:33] op_sel_hi:[1,0] neg_lo:[0,1] neg_hi:[0,1]
	v_pk_add_f32 v[104:105], v[104:105], v[32:33] op_sel_hi:[1,0] neg_lo:[0,1] neg_hi:[0,1]
	v_pk_add_f32 v[88:89], v[88:89], v[32:33] op_sel_hi:[1,0] neg_lo:[0,1] neg_hi:[0,1]
	v_pk_add_f32 v[106:107], v[106:107], v[32:33] op_sel_hi:[1,0] neg_lo:[0,1] neg_hi:[0,1]
	v_pk_add_f32 v[90:91], v[90:91], v[32:33] op_sel_hi:[1,0] neg_lo:[0,1] neg_hi:[0,1]
	v_pk_add_f32 v[108:109], v[108:109], v[32:33] op_sel_hi:[1,0] neg_lo:[0,1] neg_hi:[0,1]
	v_pk_add_f32 v[92:93], v[92:93], v[32:33] op_sel_hi:[1,0] neg_lo:[0,1] neg_hi:[0,1]
	v_pk_add_f32 v[110:111], v[110:111], v[32:33] op_sel_hi:[1,0] neg_lo:[0,1] neg_hi:[0,1]
	v_pk_add_f32 v[94:95], v[94:95], v[32:33] op_sel_hi:[1,0] neg_lo:[0,1] neg_hi:[0,1]
	v_xor_b32_e32 v32, 0x80000000, v137
	s_andn2_b64 s[2:3], s[2:3], exec
	s_and_b64 s[4:5], s[4:5], exec
	v_mul_f32_e32 v138, v138, v34
	v_pk_mul_f32 v[30:31], v[30:31], v[34:35] op_sel_hi:[1,0]
	v_pk_mul_f32 v[28:29], v[28:29], v[34:35] op_sel_hi:[1,0]
	v_pk_mul_f32 v[26:27], v[26:27], v[34:35] op_sel_hi:[1,0]
	v_pk_mul_f32 v[24:25], v[24:25], v[34:35] op_sel_hi:[1,0]
	v_pk_mul_f32 v[22:23], v[22:23], v[34:35] op_sel_hi:[1,0]
	v_pk_mul_f32 v[20:21], v[20:21], v[34:35] op_sel_hi:[1,0]
	v_pk_mul_f32 v[18:19], v[18:19], v[34:35] op_sel_hi:[1,0]
	v_pk_mul_f32 v[16:17], v[16:17], v[34:35] op_sel_hi:[1,0]
	v_pk_mul_f32 v[14:15], v[14:15], v[34:35] op_sel_hi:[1,0]
	v_pk_mul_f32 v[12:13], v[12:13], v[34:35] op_sel_hi:[1,0]
	v_pk_mul_f32 v[10:11], v[10:11], v[34:35] op_sel_hi:[1,0]
	v_pk_mul_f32 v[8:9], v[8:9], v[34:35] op_sel_hi:[1,0]
	v_pk_mul_f32 v[6:7], v[6:7], v[34:35] op_sel_hi:[1,0]
	v_pk_mul_f32 v[4:5], v[4:5], v[34:35] op_sel_hi:[1,0]
	v_pk_mul_f32 v[2:3], v[2:3], v[34:35] op_sel_hi:[1,0]
	v_pk_mul_f32 v[0:1], v[0:1], v[34:35] op_sel_hi:[1,0]
	v_mov_b32_e32 v33, v32
	v_mov_b32_e32 v34, v32
	v_mov_b32_e32 v35, v32
	v_mov_b32_e32 v36, v32
	v_mov_b32_e32 v37, v32
	v_mov_b32_e32 v38, v32
	v_mov_b32_e32 v39, v32
	v_mov_b32_e32 v40, v32
	v_mov_b32_e32 v41, v32
	v_mov_b32_e32 v42, v32
	v_mov_b32_e32 v43, v32
	v_mov_b32_e32 v44, v32
	v_mov_b32_e32 v45, v32
	v_mov_b32_e32 v46, v32
	v_mov_b32_e32 v47, v32
	s_or_b64 s[2:3], s[2:3], s[4:5]
	s_branch .LBB0_730

.LBB0_746:
	s_add_i32 s4, s17, -3
	s_min_u32 s4, s4, s40
	s_mul_hi_u32 s5, s4, 0x55555556
	s_mul_i32 s5, s5, 3
	s_sub_i32 s4, s4, s5
	s_mulk_i32 s4, 0x3000
	v_add_u32_e32 v88, s4, v135
	ds_read_b128 v[84:87], v88
	ds_read_b128 v[124:127], v88 offset:512
	ds_read_b128 v[80:83], v88 offset:2048
	ds_read_b128 v[120:123], v88 offset:2560
	s_nop 0
	v_max3_f32 v88, v48, v64, v49
	v_max3_f32 v89, v65, v50, v66
	s_nop 0
	v_max3_f32 v88, v88, v51, v67
	v_max3_f32 v89, v89, v52, v68
	s_nop 0
	v_max3_f32 v88, v88, v53, v69
	v_max3_f32 v89, v89, v54, v70
	s_nop 0
	v_max3_f32 v88, v88, v55, v71
	v_max3_f32 v89, v89, v56, v72
	s_nop 0
	v_max3_f32 v88, v88, v57, v73
	v_max3_f32 v89, v89, v58, v74
	s_nop 0
	v_max3_f32 v88, v88, v59, v75
	v_max3_f32 v89, v89, v60, v76
	s_nop 0
	v_max3_f32 v88, v88, v61, v77
	v_max3_f32 v89, v89, v62, v78
	s_nop 0
	v_max3_f32 v88, v88, v63, v79
	s_nop 0
	s_nop 1
	s_nop 0
	v_max_f32_e32 v89, v89, v89
	v_max_f32_e32 v88, v88, v88
	v_max_f32_e32 v88, v88, v89
	v_mov_b32_e32 v89, v88
	s_nop 1
	v_permlane32_swap_b32_e32 v88, v89
	v_max_f32_e32 v89, v89, v89
	v_max_f32_e32 v88, v88, v88
	v_max_f32_e32 v88, v88, v89
	v_cmp_lt_f32_e32 vcc, s97, v88
	v_cmp_lg_f32_e64 s[4:5], s96, v88
	s_nop 0
	v_cndmask_b32_e64 v89, 0, 1, vcc
	v_cndmask_b32_e64 v90, 0, 1, s[4:5]
	v_cndmask_b32_e64 v89, v90, v89, s[2:3]
	v_and_b32_e32 v89, 1, v89
	v_cmp_eq_u32_e64 s[6:7], 1, v89
	v_cmp_ne_u32_e32 vcc, 0, v89
	s_cbranch_vccz .LBB0_748
	v_cndmask_b32_e64 v32, 0, v88, s[6:7]
	v_exp_f32_e64 v34, -v32
	s_or_b64 s[4:5], s[2:3], s[4:5]
	v_add_f32_e32 v138, v138, v32
	v_pk_add_f32 v[48:49], v[48:49], v[32:33] op_sel_hi:[1,0] neg_lo:[0,1] neg_hi:[0,1]
	v_pk_add_f32 v[64:65], v[64:65], v[32:33] op_sel_hi:[1,0] neg_lo:[0,1] neg_hi:[0,1]
	v_pk_add_f32 v[50:51], v[50:51], v[32:33] op_sel_hi:[1,0] neg_lo:[0,1] neg_hi:[0,1]
	v_pk_add_f32 v[66:67], v[66:67], v[32:33] op_sel_hi:[1,0] neg_lo:[0,1] neg_hi:[0,1]
	v_pk_add_f32 v[52:53], v[52:53], v[32:33] op_sel_hi:[1,0] neg_lo:[0,1] neg_hi:[0,1]
	v_pk_add_f32 v[68:69], v[68:69], v[32:33] op_sel_hi:[1,0] neg_lo:[0,1] neg_hi:[0,1]
	v_pk_add_f32 v[54:55], v[54:55], v[32:33] op_sel_hi:[1,0] neg_lo:[0,1] neg_hi:[0,1]
	v_pk_add_f32 v[70:71], v[70:71], v[32:33] op_sel_hi:[1,0] neg_lo:[0,1] neg_hi:[0,1]
	v_pk_add_f32 v[56:57], v[56:57], v[32:33] op_sel_hi:[1,0] neg_lo:[0,1] neg_hi:[0,1]
	v_pk_add_f32 v[72:73], v[72:73], v[32:33] op_sel_hi:[1,0] neg_lo:[0,1] neg_hi:[0,1]
	v_pk_add_f32 v[58:59], v[58:59], v[32:33] op_sel_hi:[1,0] neg_lo:[0,1] neg_hi:[0,1]
	v_pk_add_f32 v[74:75], v[74:75], v[32:33] op_sel_hi:[1,0] neg_lo:[0,1] neg_hi:[0,1]
	v_pk_add_f32 v[60:61], v[60:61], v[32:33] op_sel_hi:[1,0] neg_lo:[0,1] neg_hi:[0,1]
	v_pk_add_f32 v[76:77], v[76:77], v[32:33] op_sel_hi:[1,0] neg_lo:[0,1] neg_hi:[0,1]
	v_pk_add_f32 v[62:63], v[62:63], v[32:33] op_sel_hi:[1,0] neg_lo:[0,1] neg_hi:[0,1]
	v_pk_add_f32 v[78:79], v[78:79], v[32:33] op_sel_hi:[1,0] neg_lo:[0,1] neg_hi:[0,1]
	v_xor_b32_e32 v32, 0x80000000, v138
	s_andn2_b64 s[2:3], s[2:3], exec
	s_and_b64 s[4:5], s[4:5], exec
	v_mul_f32_e32 v139, v139, v34
	v_pk_mul_f32 v[30:31], v[30:31], v[34:35] op_sel_hi:[1,0]
	v_pk_mul_f32 v[28:29], v[28:29], v[34:35] op_sel_hi:[1,0]
	v_pk_mul_f32 v[26:27], v[26:27], v[34:35] op_sel_hi:[1,0]
	v_pk_mul_f32 v[24:25], v[24:25], v[34:35] op_sel_hi:[1,0]
	v_pk_mul_f32 v[22:23], v[22:23], v[34:35] op_sel_hi:[1,0]
	v_pk_mul_f32 v[20:21], v[20:21], v[34:35] op_sel_hi:[1,0]
	v_pk_mul_f32 v[18:19], v[18:19], v[34:35] op_sel_hi:[1,0]
	v_pk_mul_f32 v[16:17], v[16:17], v[34:35] op_sel_hi:[1,0]
	v_pk_mul_f32 v[14:15], v[14:15], v[34:35] op_sel_hi:[1,0]
	v_pk_mul_f32 v[12:13], v[12:13], v[34:35] op_sel_hi:[1,0]
	v_pk_mul_f32 v[10:11], v[10:11], v[34:35] op_sel_hi:[1,0]
	v_pk_mul_f32 v[8:9], v[8:9], v[34:35] op_sel_hi:[1,0]
	v_pk_mul_f32 v[6:7], v[6:7], v[34:35] op_sel_hi:[1,0]
	v_pk_mul_f32 v[4:5], v[4:5], v[34:35] op_sel_hi:[1,0]
	v_pk_mul_f32 v[2:3], v[2:3], v[34:35] op_sel_hi:[1,0]
	v_pk_mul_f32 v[0:1], v[0:1], v[34:35] op_sel_hi:[1,0]
	v_mov_b32_e32 v33, v32
	v_mov_b32_e32 v34, v32
	v_mov_b32_e32 v35, v32
	v_mov_b32_e32 v36, v32
	v_mov_b32_e32 v37, v32
	v_mov_b32_e32 v38, v32
	v_mov_b32_e32 v39, v32
	v_mov_b32_e32 v40, v32
	v_mov_b32_e32 v41, v32
	v_mov_b32_e32 v42, v32
	v_mov_b32_e32 v43, v32
	v_mov_b32_e32 v44, v32
	v_mov_b32_e32 v45, v32
	v_mov_b32_e32 v46, v32
	v_mov_b32_e32 v47, v32
	s_or_b64 s[2:3], s[2:3], s[4:5]

.LBB0_751:
	v_add3_u32 v48, s21, v133, v134
	ds_read_b128 v[68:71], v48
	ds_read_b128 v[124:127], v48 offset:512
	ds_read_b128 v[64:67], v48 offset:2048
	ds_read_b128 v[120:123], v48 offset:2560
	s_nop 0
	v_max3_f32 v48, v96, v80, v97
	v_max3_f32 v49, v81, v98, v82
	s_nop 0
	v_max3_f32 v48, v48, v99, v83
	v_max3_f32 v49, v49, v100, v84
	s_nop 0
	v_max3_f32 v48, v48, v101, v85
	v_max3_f32 v49, v49, v102, v86
	s_nop 0
	v_max3_f32 v48, v48, v103, v87
	v_max3_f32 v49, v49, v104, v88
	s_nop 0
	v_max3_f32 v48, v48, v105, v89
	v_max3_f32 v49, v49, v106, v90
	s_nop 0
	v_max3_f32 v48, v48, v107, v91
	v_max3_f32 v49, v49, v108, v92
	s_nop 0
	v_max3_f32 v48, v48, v109, v93
	v_max3_f32 v49, v49, v110, v94
	s_nop 0
	v_max3_f32 v48, v48, v111, v95
	s_nop 0
	s_nop 1
	s_nop 0
	v_max_f32_e32 v49, v49, v49
	v_max_f32_e32 v48, v48, v48
	v_max_f32_e32 v48, v48, v49
	v_mov_b32_e32 v49, v48
	s_nop 1
	v_permlane32_swap_b32_e32 v48, v49
	v_max_f32_e32 v49, v49, v49
	v_max_f32_e32 v48, v48, v48
	v_max_f32_e32 v48, v48, v49
	v_cmp_lt_f32_e32 vcc, s97, v48
	v_cmp_lg_f32_e64 s[4:5], s96, v48
	s_nop 0
	v_cndmask_b32_e64 v49, 0, 1, vcc
	v_cndmask_b32_e64 v50, 0, 1, s[4:5]
	v_cndmask_b32_e64 v49, v50, v49, s[2:3]
	v_and_b32_e32 v49, 1, v49
	v_cmp_eq_u32_e64 s[6:7], 1, v49
	v_cmp_ne_u32_e32 vcc, 0, v49
	s_cbranch_vccz .LBB0_742
	v_cndmask_b32_e64 v32, 0, v48, s[6:7]
	v_exp_f32_e64 v34, -v32
	s_or_b64 s[4:5], s[2:3], s[4:5]
	v_add_f32_e32 v138, v138, v32
	v_pk_add_f32 v[96:97], v[96:97], v[32:33] op_sel_hi:[1,0] neg_lo:[0,1] neg_hi:[0,1]
	v_pk_add_f32 v[80:81], v[80:81], v[32:33] op_sel_hi:[1,0] neg_lo:[0,1] neg_hi:[0,1]
	v_pk_add_f32 v[98:99], v[98:99], v[32:33] op_sel_hi:[1,0] neg_lo:[0,1] neg_hi:[0,1]
	v_pk_add_f32 v[82:83], v[82:83], v[32:33] op_sel_hi:[1,0] neg_lo:[0,1] neg_hi:[0,1]
	v_pk_add_f32 v[100:101], v[100:101], v[32:33] op_sel_hi:[1,0] neg_lo:[0,1] neg_hi:[0,1]
	v_pk_add_f32 v[84:85], v[84:85], v[32:33] op_sel_hi:[1,0] neg_lo:[0,1] neg_hi:[0,1]
	v_pk_add_f32 v[102:103], v[102:103], v[32:33] op_sel_hi:[1,0] neg_lo:[0,1] neg_hi:[0,1]
	v_pk_add_f32 v[86:87], v[86:87], v[32:33] op_sel_hi:[1,0] neg_lo:[0,1] neg_hi:[0,1]
	v_pk_add_f32 v[104:105], v[104:105], v[32:33] op_sel_hi:[1,0] neg_lo:[0,1] neg_hi:[0,1]
	v_pk_add_f32 v[88:89], v[88:89], v[32:33] op_sel_hi:[1,0] neg_lo:[0,1] neg_hi:[0,1]
	v_pk_add_f32 v[106:107], v[106:107], v[32:33] op_sel_hi:[1,0] neg_lo:[0,1] neg_hi:[0,1]
	v_pk_add_f32 v[90:91], v[90:91], v[32:33] op_sel_hi:[1,0] neg_lo:[0,1] neg_hi:[0,1]
	v_pk_add_f32 v[108:109], v[108:109], v[32:33] op_sel_hi:[1,0] neg_lo:[0,1] neg_hi:[0,1]
	v_pk_add_f32 v[92:93], v[92:93], v[32:33] op_sel_hi:[1,0] neg_lo:[0,1] neg_hi:[0,1]
	v_pk_add_f32 v[110:111], v[110:111], v[32:33] op_sel_hi:[1,0] neg_lo:[0,1] neg_hi:[0,1]
	v_pk_add_f32 v[94:95], v[94:95], v[32:33] op_sel_hi:[1,0] neg_lo:[0,1] neg_hi:[0,1]
	v_xor_b32_e32 v32, 0x80000000, v138
	s_andn2_b64 s[2:3], s[2:3], exec
	s_and_b64 s[4:5], s[4:5], exec
	v_mul_f32_e32 v139, v139, v34
	v_pk_mul_f32 v[30:31], v[30:31], v[34:35] op_sel_hi:[1,0]
	v_pk_mul_f32 v[28:29], v[28:29], v[34:35] op_sel_hi:[1,0]
	v_pk_mul_f32 v[26:27], v[26:27], v[34:35] op_sel_hi:[1,0]
	v_pk_mul_f32 v[24:25], v[24:25], v[34:35] op_sel_hi:[1,0]
	v_pk_mul_f32 v[22:23], v[22:23], v[34:35] op_sel_hi:[1,0]
	v_pk_mul_f32 v[20:21], v[20:21], v[34:35] op_sel_hi:[1,0]
	v_pk_mul_f32 v[18:19], v[18:19], v[34:35] op_sel_hi:[1,0]
	v_pk_mul_f32 v[16:17], v[16:17], v[34:35] op_sel_hi:[1,0]
	v_pk_mul_f32 v[14:15], v[14:15], v[34:35] op_sel_hi:[1,0]
	v_pk_mul_f32 v[12:13], v[12:13], v[34:35] op_sel_hi:[1,0]
	v_pk_mul_f32 v[10:11], v[10:11], v[34:35] op_sel_hi:[1,0]
	v_pk_mul_f32 v[8:9], v[8:9], v[34:35] op_sel_hi:[1,0]
	v_pk_mul_f32 v[6:7], v[6:7], v[34:35] op_sel_hi:[1,0]
	v_pk_mul_f32 v[4:5], v[4:5], v[34:35] op_sel_hi:[1,0]
	v_pk_mul_f32 v[2:3], v[2:3], v[34:35] op_sel_hi:[1,0]
	v_pk_mul_f32 v[0:1], v[0:1], v[34:35] op_sel_hi:[1,0]
	v_mov_b32_e32 v33, v32
	v_mov_b32_e32 v34, v32
	v_mov_b32_e32 v35, v32
	v_mov_b32_e32 v36, v32
	v_mov_b32_e32 v37, v32
	v_mov_b32_e32 v38, v32
	v_mov_b32_e32 v39, v32
	v_mov_b32_e32 v40, v32
	v_mov_b32_e32 v41, v32
	v_mov_b32_e32 v42, v32
	v_mov_b32_e32 v43, v32
	v_mov_b32_e32 v44, v32
	v_mov_b32_e32 v45, v32
	v_mov_b32_e32 v46, v32
	v_mov_b32_e32 v47, v32
	s_or_b64 s[2:3], s[2:3], s[4:5]
	s_branch .LBB0_742
